# HGRN pass-3 norm and gating LayerNorm: ds_bpermute butterflies replaced by DPP moves + permlane16/32 swaps (same add tree)
# speedup vs baseline: 1.0437x; 1.0007x over previous
.LBB0_268:
	v_readlane_b32 s6, v254, 60
	v_mov_b32_e32 v58, v176
	s_and_b32 s1, s18, 0xffffff80
	v_mov_b32_e32 v0, s6
	ds_read2_b64 v[4:7], v0 offset1:1
	v_readfirstlane_b32 s7, v58
	s_ashr_i32 s0, s7, 6
	s_lshl_b64 s[8:9], s[4:5], 2
	v_and_b32_e32 v12, 63, v58
	s_waitcnt lgkmcnt(0)
	v_readfirstlane_b32 s6, v4
	v_readfirstlane_b32 s11, v5
	s_add_u32 s10, s6, s8
	s_addc_u32 s11, s11, s9
	v_readfirstlane_b32 s6, v6
	v_readfirstlane_b32 s12, v7
	s_add_u32 s8, s6, s8
	s_addc_u32 s9, s12, s9
	s_lshl_b32 s6, s0, 4
	v_lshlrev_b32_e32 v0, 4, v12
	v_mov_b32_e32 v1, v2
	s_add_i32 s38, s6, s1
	v_lshl_add_u64 v[4:5], s[10:11], 0, v[0:1]
	v_lshl_add_u64 v[0:1], s[8:9], 0, v[0:1]
	s_mul_i32 s8, s38, 0x2600
	s_mul_hi_i32 s1, s38, 0x2600
	s_add_u32 s8, s80, s8
	s_addc_u32 s9, s81, s1
	v_lshlrev_b32_e32 v12, 3, v12
	s_barrier
	global_load_dwordx2 v[34:35], v12, s[8:9] offset:3072
	s_or_b32 s1, s38, 1
	s_mul_hi_i32 s9, s1, 0x2600
	s_mulk_i32 s1, 0x2600
	s_add_u32 s8, s80, s1
	s_addc_u32 s9, s81, s9
	global_load_dwordx2 v[36:37], v12, s[8:9] offset:3072
	s_or_b32 s1, s38, 2
	s_mul_hi_i32 s9, s1, 0x2600
	s_mulk_i32 s1, 0x2600
	s_add_u32 s8, s80, s1
	s_addc_u32 s9, s81, s9
	s_or_b32 s1, s38, 3
	global_load_dwordx2 v[42:43], v12, s[8:9] offset:3072
	s_mul_hi_i32 s9, s1, 0x2600
	s_mulk_i32 s1, 0x2600
	s_add_u32 s8, s80, s1
	s_addc_u32 s9, s81, s9
	s_or_b32 s1, s38, 4
	global_load_dwordx2 v[44:45], v12, s[8:9] offset:3072
	s_mul_hi_i32 s9, s1, 0x2600
	s_mulk_i32 s1, 0x2600
	s_add_u32 s8, s80, s1
	s_addc_u32 s9, s81, s9
	s_or_b32 s1, s38, 5
	global_load_dwordx2 v[30:31], v12, s[8:9] offset:3072
	s_mul_hi_i32 s9, s1, 0x2600
	s_mulk_i32 s1, 0x2600
	s_add_u32 s8, s80, s1
	s_addc_u32 s9, s81, s9
	s_or_b32 s1, s38, 6
	global_load_dwordx2 v[32:33], v12, s[8:9] offset:3072
	s_mul_hi_i32 s9, s1, 0x2600
	s_mulk_i32 s1, 0x2600
	s_add_u32 s8, s80, s1
	s_addc_u32 s9, s81, s9
	s_or_b32 s1, s38, 7
	global_load_dwordx2 v[26:27], v12, s[8:9] offset:3072
	s_mul_hi_i32 s9, s1, 0x2600
	s_mulk_i32 s1, 0x2600
	s_add_u32 s8, s80, s1
	s_addc_u32 s9, s81, s9
	s_or_b32 s1, s38, 8
	global_load_dwordx2 v[28:29], v12, s[8:9] offset:3072
	s_mul_hi_i32 s9, s1, 0x2600
	s_mulk_i32 s1, 0x2600
	s_add_u32 s8, s80, s1
	s_addc_u32 s9, s81, s9
	s_or_b32 s1, s38, 9
	global_load_dwordx2 v[22:23], v12, s[8:9] offset:3072
	s_mul_hi_i32 s9, s1, 0x2600
	s_mulk_i32 s1, 0x2600
	s_add_u32 s8, s80, s1
	s_addc_u32 s9, s81, s9
	s_or_b32 s1, s38, 10
	global_load_dwordx2 v[24:25], v12, s[8:9] offset:3072
	s_mul_hi_i32 s9, s1, 0x2600
	s_mulk_i32 s1, 0x2600
	s_add_u32 s8, s80, s1
	s_addc_u32 s9, s81, s9
	s_or_b32 s1, s38, 11
	global_load_dwordx2 v[18:19], v12, s[8:9] offset:3072
	s_mul_hi_i32 s9, s1, 0x2600
	s_mulk_i32 s1, 0x2600
	s_add_u32 s8, s80, s1
	s_addc_u32 s9, s81, s9
	s_or_b32 s1, s38, 12
	global_load_dwordx2 v[20:21], v12, s[8:9] offset:3072
	s_mul_hi_i32 s9, s1, 0x2600
	s_mulk_i32 s1, 0x2600
	s_add_u32 s8, s80, s1
	s_addc_u32 s9, s81, s9
	s_or_b32 s1, s38, 13
	global_load_dwordx2 v[14:15], v12, s[8:9] offset:3072
	s_mul_hi_i32 s9, s1, 0x2600
	s_mulk_i32 s1, 0x2600
	s_add_u32 s8, s80, s1
	s_addc_u32 s9, s81, s9
	s_or_b32 s1, s38, 14
	global_load_dwordx2 v[16:17], v12, s[8:9] offset:3072
	s_mul_hi_i32 s9, s1, 0x2600
	s_mulk_i32 s1, 0x2600
	s_add_u32 s8, s80, s1
	s_addc_u32 s9, s81, s9
	s_or_b32 s1, s38, 15
	flat_load_dwordx4 v[8:11], v[0:1]
	s_waitcnt vmcnt(0)
	v_lshlrev_b32_e32 v39, 16, v34
	global_load_dwordx2 v[0:1], v12, s[8:9] offset:3072
	s_mul_hi_i32 s9, s1, 0x2600
	s_mulk_i32 s1, 0x2600
	s_add_u32 s8, s80, s1
	s_addc_u32 s9, s81, s9
	s_lshl_b32 s0, s0, 5
	s_add_i32 s10, s0, 0
	v_cmp_lt_i32_e64 s[0:1], v182, v181
	v_and_b32_e32 v53, 0xffff0000, v34
	v_lshlrev_b32_e32 v38, 2, v58
	v_cndmask_b32_e64 v34, v179, v182, s[0:1]
	v_cmp_lt_i32_e64 s[0:1], v183, v181
	v_lshlrev_b32_e32 v65, 2, v34
	v_and_b32_e32 v59, 60, v38
	v_cndmask_b32_e64 v34, v179, v183, s[0:1]
	v_cmp_lt_i32_e64 s[0:1], v184, v181
	v_lshlrev_b32_e32 v64, 2, v34
	v_lshlrev_b32_e32 v55, 16, v35
	v_cndmask_b32_e64 v34, v179, v184, s[0:1]
	v_cmp_lt_i32_e64 s[0:1], v185, v181
	v_lshlrev_b32_e32 v63, 2, v34
	v_lshlrev_b32_e32 v38, 16, v36
	v_cndmask_b32_e64 v34, v179, v185, s[0:1]
	v_cmp_lt_i32_e64 s[0:1], v186, v181
	v_lshlrev_b32_e32 v62, 2, v34
	v_and_b32_e32 v52, 0xffff0000, v36
	v_cndmask_b32_e64 v34, v179, v186, s[0:1]
	v_cmp_lt_i32_e64 s[0:1], v187, v181
	v_lshlrev_b32_e32 v61, 2, v34
	v_lshlrev_b32_e32 v54, 16, v37
	v_cndmask_b32_e64 v34, v179, v187, s[0:1]
	v_lshlrev_b32_e32 v60, 2, v34
	v_and_b32_e32 v35, 0xffff0000, v35
	v_and_b32_e32 v34, 0xffff0000, v37
	v_pk_add_f32 v[36:37], v[38:39], v[52:53]
	v_pk_add_f32 v[40:41], v[54:55], v[34:35]
	v_lshlrev_b32_e32 v51, 16, v42
	v_pk_add_f32 v[36:37], v[36:37], v[40:41]
	s_nop 1
	v_mov_b32_dpp v41, v37 quad_perm:[1,0,3,2] row_mask:0xf bank_mask:0xf
	v_mov_b32_dpp v40, v36 quad_perm:[1,0,3,2] row_mask:0xf bank_mask:0xf
	v_and_b32_e32 v49, 0xffff0000, v42
	v_lshlrev_b32_e32 v47, 16, v43
	v_lshlrev_b32_e32 v50, 16, v44
	v_and_b32_e32 v48, 0xffff0000, v44
	s_waitcnt lgkmcnt(0)
	v_pk_add_f32 v[36:37], v[36:37], v[40:41]
	s_nop 1
	v_mov_b32_dpp v41, v37 quad_perm:[2,3,0,1] row_mask:0xf bank_mask:0xf
	v_mov_b32_dpp v40, v36 quad_perm:[2,3,0,1] row_mask:0xf bank_mask:0xf
	v_lshlrev_b32_e32 v46, 16, v45
	s_mov_b32 s12, 0x3b800000
	v_and_b32_e32 v43, 0xffff0000, v43
	v_and_b32_e32 v42, 0xffff0000, v45
	s_waitcnt lgkmcnt(0)
	v_pk_add_f32 v[36:37], v[36:37], v[40:41]
	s_nop 1
	v_mov_b32_dpp v41, v37 row_half_mirror row_mask:0xf bank_mask:0xf
	v_mov_b32_dpp v40, v36 row_half_mirror row_mask:0xf bank_mask:0xf
	v_pk_add_f32 v[44:45], v[50:51], v[48:49]
	flat_load_dwordx4 v[4:7], v[4:5]
	v_bfe_u32 v3, v58, 4, 2
	global_load_dwordx2 v[12:13], v12, s[8:9] offset:3072
	s_waitcnt lgkmcnt(0)
	v_pk_add_f32 v[36:37], v[36:37], v[40:41]
	s_nop 1
	v_mov_b32_dpp v41, v37 row_mirror row_mask:0xf bank_mask:0xf
	v_mov_b32_dpp v40, v36 row_mirror row_mask:0xf bank_mask:0xf
	s_and_b32 s47, s46, 3
	v_cmp_eq_u32_e32 vcc, s47, v3
	s_waitcnt lgkmcnt(0)
	v_pk_add_f32 v[36:37], v[36:37], v[40:41]
	v_mov_b32_e32 v41, v37
	s_nop 1
	v_permlane16_swap_b32_e32 v37, v41
	v_mov_b32_e32 v40, v36
	s_nop 1
	v_permlane16_swap_b32_e32 v36, v40
	s_waitcnt lgkmcnt(0)
	v_pk_add_f32 v[36:37], v[36:37], v[40:41]
	v_mov_b32_e32 v41, v37
	s_nop 1
	v_permlane32_swap_b32_e32 v37, v41
	v_mov_b32_e32 v40, v36
	s_nop 1
	v_permlane32_swap_b32_e32 v36, v40
	s_waitcnt lgkmcnt(0)
	v_pk_add_f32 v[56:57], v[36:37], v[40:41]
	s_nop 0
	v_pk_fma_f32 v[40:41], v[56:57], s[12:13], v[38:39] op_sel_hi:[1,0,1] neg_lo:[1,0,0] neg_hi:[1,0,0]
	v_pk_fma_f32 v[38:39], v[56:57], s[12:13], v[52:53] op_sel_hi:[1,0,1] neg_lo:[1,0,0] neg_hi:[1,0,0]
	v_pk_add_f32 v[52:53], v[46:47], v[42:43]
	v_pk_fma_f32 v[34:35], v[56:57], s[12:13], v[34:35] op_sel_hi:[1,0,1] neg_lo:[1,0,0] neg_hi:[1,0,0]
	v_pk_add_f32 v[44:45], v[44:45], v[52:53]
	s_nop 1
	v_mov_b32_dpp v53, v45 quad_perm:[1,0,3,2] row_mask:0xf bank_mask:0xf
	v_mov_b32_dpp v52, v44 quad_perm:[1,0,3,2] row_mask:0xf bank_mask:0xf
	v_pk_fma_f32 v[36:37], v[56:57], s[12:13], v[54:55] op_sel_hi:[1,0,1] neg_lo:[1,0,0] neg_hi:[1,0,0]
	s_waitcnt lgkmcnt(0)
	v_pk_add_f32 v[44:45], v[44:45], v[52:53]
	s_nop 1
	v_mov_b32_dpp v53, v45 quad_perm:[2,3,0,1] row_mask:0xf bank_mask:0xf
	v_mov_b32_dpp v52, v44 quad_perm:[2,3,0,1] row_mask:0xf bank_mask:0xf
	s_waitcnt lgkmcnt(0)
	v_pk_add_f32 v[44:45], v[44:45], v[52:53]
	s_nop 1
	v_mov_b32_dpp v53, v45 row_half_mirror row_mask:0xf bank_mask:0xf
	v_mov_b32_dpp v52, v44 row_half_mirror row_mask:0xf bank_mask:0xf
	s_waitcnt lgkmcnt(0)
	v_pk_add_f32 v[44:45], v[44:45], v[52:53]
	s_nop 1
	v_mov_b32_dpp v53, v45 row_mirror row_mask:0xf bank_mask:0xf
	v_mov_b32_dpp v52, v44 row_mirror row_mask:0xf bank_mask:0xf
	s_waitcnt lgkmcnt(0)
	v_pk_add_f32 v[44:45], v[44:45], v[52:53]
	v_mov_b32_e32 v53, v45
	s_nop 1
	v_permlane16_swap_b32_e32 v45, v53
	v_mov_b32_e32 v52, v44
	s_nop 1
	v_permlane16_swap_b32_e32 v44, v52
	s_waitcnt lgkmcnt(0)
	v_pk_add_f32 v[44:45], v[44:45], v[52:53]
	v_mov_b32_e32 v53, v45
	s_nop 1
	v_permlane32_swap_b32_e32 v45, v53
	v_mov_b32_e32 v52, v44
	s_nop 1
	v_permlane32_swap_b32_e32 v44, v52
	s_waitcnt lgkmcnt(0)
	v_pk_add_f32 v[52:53], v[44:45], v[52:53]
	s_nop 0
	v_pk_fma_f32 v[50:51], v[52:53], s[12:13], v[50:51] op_sel_hi:[1,0,1] neg_lo:[1,0,0] neg_hi:[1,0,0]
	v_pk_fma_f32 v[48:49], v[52:53], s[12:13], v[48:49] op_sel_hi:[1,0,1] neg_lo:[1,0,0] neg_hi:[1,0,0]
	v_pk_fma_f32 v[44:45], v[52:53], s[12:13], v[46:47] op_sel_hi:[1,0,1] neg_lo:[1,0,0] neg_hi:[1,0,0]
	v_pk_fma_f32 v[42:43], v[52:53], s[12:13], v[42:43] op_sel_hi:[1,0,1] neg_lo:[1,0,0] neg_hi:[1,0,0]
	v_pk_mul_f32 v[46:47], v[38:39], v[38:39]
	v_pk_mul_f32 v[52:53], v[34:35], v[34:35]
	v_pk_fma_f32 v[46:47], v[40:41], v[40:41], v[46:47]
	v_pk_fma_f32 v[52:53], v[36:37], v[36:37], v[52:53]
	v_pk_mul_f32 v[54:55], v[42:43], v[42:43]
	v_pk_add_f32 v[46:47], v[46:47], v[52:53]
	s_nop 1
	v_mov_b32_dpp v53, v47 quad_perm:[1,0,3,2] row_mask:0xf bank_mask:0xf
	v_mov_b32_dpp v52, v46 quad_perm:[1,0,3,2] row_mask:0xf bank_mask:0xf
	v_pk_fma_f32 v[54:55], v[44:45], v[44:45], v[54:55]
	s_waitcnt lgkmcnt(0)
	v_pk_add_f32 v[46:47], v[46:47], v[52:53]
	s_nop 1
	v_mov_b32_dpp v53, v47 quad_perm:[2,3,0,1] row_mask:0xf bank_mask:0xf
	v_mov_b32_dpp v52, v46 quad_perm:[2,3,0,1] row_mask:0xf bank_mask:0xf
	s_waitcnt lgkmcnt(0)
	v_pk_add_f32 v[46:47], v[46:47], v[52:53]
	s_nop 1
	v_mov_b32_dpp v53, v47 row_half_mirror row_mask:0xf bank_mask:0xf
	v_mov_b32_dpp v52, v46 row_half_mirror row_mask:0xf bank_mask:0xf
	s_waitcnt lgkmcnt(0)
	v_pk_add_f32 v[46:47], v[46:47], v[52:53]
	s_nop 1
	v_mov_b32_dpp v53, v47 row_mirror row_mask:0xf bank_mask:0xf
	v_mov_b32_dpp v52, v46 row_mirror row_mask:0xf bank_mask:0xf
	s_waitcnt lgkmcnt(0)
	v_pk_add_f32 v[46:47], v[46:47], v[52:53]
	v_mov_b32_e32 v53, v47
	s_nop 1
	v_permlane16_swap_b32_e32 v47, v53
	v_mov_b32_e32 v52, v46
	s_nop 1
	v_permlane16_swap_b32_e32 v46, v52
	s_waitcnt lgkmcnt(0)
	v_pk_add_f32 v[46:47], v[46:47], v[52:53]
	v_pk_mul_f32 v[52:53], v[48:49], v[48:49]
	v_mov_b32_e32 v57, v47
	s_nop 1
	v_permlane32_swap_b32_e32 v47, v57
	v_pk_fma_f32 v[52:53], v[50:51], v[50:51], v[52:53]
	v_mov_b32_e32 v56, v46
	s_nop 1
	v_permlane32_swap_b32_e32 v46, v56
	v_pk_add_f32 v[52:53], v[52:53], v[54:55]
	s_nop 1
	v_mov_b32_dpp v55, v53 quad_perm:[1,0,3,2] row_mask:0xf bank_mask:0xf
	v_mov_b32_dpp v54, v52 quad_perm:[1,0,3,2] row_mask:0xf bank_mask:0xf
	s_waitcnt lgkmcnt(0)
	v_pk_add_f32 v[52:53], v[52:53], v[54:55]
	s_nop 1
	v_mov_b32_dpp v55, v53 quad_perm:[2,3,0,1] row_mask:0xf bank_mask:0xf
	v_mov_b32_dpp v54, v52 quad_perm:[2,3,0,1] row_mask:0xf bank_mask:0xf
	s_waitcnt lgkmcnt(0)
	v_pk_add_f32 v[52:53], v[52:53], v[54:55]
	s_nop 1
	v_mov_b32_dpp v55, v53 row_half_mirror row_mask:0xf bank_mask:0xf
	v_mov_b32_dpp v54, v52 row_half_mirror row_mask:0xf bank_mask:0xf
	s_waitcnt lgkmcnt(0)
	v_pk_add_f32 v[52:53], v[52:53], v[54:55]
	s_nop 1
	v_mov_b32_dpp v55, v53 row_mirror row_mask:0xf bank_mask:0xf
	v_mov_b32_dpp v54, v52 row_mirror row_mask:0xf bank_mask:0xf
	s_waitcnt lgkmcnt(0)
	v_pk_add_f32 v[52:53], v[52:53], v[54:55]
	v_mov_b32_e32 v55, v53
	s_nop 1
	v_permlane16_swap_b32_e32 v53, v55
	v_mov_b32_e32 v54, v52
	s_nop 1
	v_permlane16_swap_b32_e32 v52, v54
	s_waitcnt lgkmcnt(0)
	v_pk_add_f32 v[52:53], v[52:53], v[54:55]
	v_mov_b32_e32 v55, v53
	s_nop 1
	v_permlane32_swap_b32_e32 v53, v55
	v_mov_b32_e32 v54, v52
	s_nop 1
	v_permlane32_swap_b32_e32 v52, v54
	s_and_saveexec_b64 s[8:9], vcc
	s_cbranch_execz .LBB0_270
	s_mov_b32 s0, 0x358637bd
	v_pk_add_f32 v[46:47], v[46:47], v[56:57]
	v_mov_b64_e32 v[56:57], s[0:1]
	v_pk_fma_f32 v[46:47], v[46:47], s[12:13], v[56:57] op_sel_hi:[1,0,0]
	s_movk_i32 s11, 0x110
	v_mul_f32_e32 v66, 0x4b800000, v47
	v_cmp_gt_f32_e64 s[0:1], s34, v47
	s_nop 1
	v_cndmask_b32_e64 v47, v47, v66, s[0:1]
	v_rsq_f32_e32 v47, v47
	v_mov_b32_e32 v66, s10
	v_mad_u32_u24 v66, v59, s11, v66
	v_mul_f32_e32 v67, 0x45800000, v47
	v_cndmask_b32_e64 v47, v47, v67, s[0:1]
	v_mul_f32_e32 v41, v41, v47
	v_mul_f32_e32 v39, v39, v47
	v_mul_f32_e32 v37, v37, v47
	s_waitcnt vmcnt(0)
	v_fma_f32 v41, v4, v41, v8
	v_fma_f32 v39, v5, v39, v9
	v_fma_f32 v37, v6, v37, v10
	v_cvt_pk_bf16_f32 v41, v41, v2
	ds_write_b16 v66, v41
	v_cvt_pk_bf16_f32 v39, v39, v2
	ds_write_b16 v66, v39 offset:272
	v_cvt_pk_bf16_f32 v37, v37, v2
	ds_write_b16 v66, v37 offset:544
	v_mul_f32_e32 v37, 0x4b800000, v46
	v_cmp_gt_f32_e64 s[0:1], s34, v46
	v_mul_f32_e32 v35, v35, v47
	v_fma_f32 v35, v7, v35, v11
	v_cndmask_b32_e64 v37, v46, v37, s[0:1]
	v_rsq_f32_e32 v37, v37
	v_cvt_pk_bf16_f32 v35, v35, v2
	ds_write_b16 v66, v35 offset:816
	v_mul_f32_e32 v35, 0x45800000, v37
	v_cndmask_b32_e64 v35, v37, v35, s[0:1]
	v_mul_f32_e32 v37, v40, v35
	v_fma_f32 v37, v4, v37, v8
	v_cvt_pk_bf16_f32 v37, v37, v2
	ds_write_b16 v66, v37 offset:2
	v_mul_f32_e32 v37, v38, v35
	v_mul_f32_e32 v36, v36, v35
	v_fma_f32 v37, v5, v37, v9
	v_fma_f32 v36, v6, v36, v10
	v_cvt_pk_bf16_f32 v37, v37, v2
	ds_write_b16 v66, v37 offset:274
	v_cvt_pk_bf16_f32 v36, v36, v2
	ds_write_b16 v66, v36 offset:546
	v_mul_f32_e32 v36, v34, v35
	s_waitcnt lgkmcnt(7)
	v_pk_add_f32 v[34:35], v[52:53], v[54:55]
	v_fma_f32 v36, v7, v36, v11
	v_pk_fma_f32 v[34:35], v[34:35], s[12:13], v[56:57] op_sel_hi:[1,0,0]
	v_cvt_pk_bf16_f32 v36, v36, v2
	ds_write_b16 v66, v36 offset:818
	v_mul_f32_e32 v37, 0x4b800000, v35
	v_cmp_gt_f32_e64 s[0:1], s34, v35
	s_nop 1
	v_cndmask_b32_e64 v35, v35, v37, s[0:1]
	v_rsq_f32_e32 v35, v35
	s_nop 0
	v_mul_f32_e32 v36, 0x45800000, v35
	v_cndmask_b32_e64 v35, v35, v36, s[0:1]
	v_mul_f32_e32 v36, v51, v35
	v_fma_f32 v36, v4, v36, v8
	v_cvt_pk_bf16_f32 v36, v36, v2
	ds_write_b16 v66, v36 offset:4
	v_mul_f32_e32 v36, v49, v35
	v_fma_f32 v36, v5, v36, v9
	v_cvt_pk_bf16_f32 v36, v36, v2
	ds_write_b16 v66, v36 offset:276
	v_mul_f32_e32 v36, v45, v35
	v_fma_f32 v36, v6, v36, v10
	v_cvt_pk_bf16_f32 v36, v36, v2
	ds_write_b16 v66, v36 offset:548
	v_mul_f32_e32 v36, 0x4b800000, v34
	v_cmp_gt_f32_e64 s[0:1], s34, v34
	v_mul_f32_e32 v35, v43, v35
	v_fma_f32 v35, v7, v35, v11
	v_cndmask_b32_e64 v34, v34, v36, s[0:1]
	v_rsq_f32_e32 v34, v34
	v_cvt_pk_bf16_f32 v35, v35, v2
	ds_write_b16 v66, v35 offset:820
	v_mul_f32_e32 v35, 0x45800000, v34
	v_cndmask_b32_e64 v34, v34, v35, s[0:1]
	v_mul_f32_e32 v35, v50, v34
	v_fma_f32 v35, v4, v35, v8
	v_cvt_pk_bf16_f32 v35, v35, v2
	ds_write_b16 v66, v35 offset:6
	v_mul_f32_e32 v35, v48, v34
	v_fma_f32 v35, v5, v35, v9
	v_cvt_pk_bf16_f32 v35, v35, v2
	ds_write_b16 v66, v35 offset:278
	v_mul_f32_e32 v35, v44, v34
	v_mul_f32_e32 v34, v42, v34
	v_fma_f32 v35, v6, v35, v10
	v_fma_f32 v34, v7, v34, v11
	v_cvt_pk_bf16_f32 v35, v35, v2
	ds_write_b16 v66, v35 offset:550
	v_cvt_pk_bf16_f32 v34, v34, v2
	ds_write_b16 v66, v34 offset:822
.LBB0_270:
	s_or_b64 exec, exec, s[8:9]
	v_lshlrev_b32_e32 v35, 16, v30
	v_and_b32_e32 v45, 0xffff0000, v30
	v_lshlrev_b32_e32 v47, 16, v31
	v_lshlrev_b32_e32 v34, 16, v32
	v_and_b32_e32 v44, 0xffff0000, v32
	v_lshlrev_b32_e32 v46, 16, v33
	v_and_b32_e32 v31, 0xffff0000, v31
	v_and_b32_e32 v30, 0xffff0000, v33
	v_pk_add_f32 v[32:33], v[34:35], v[44:45]
	v_pk_add_f32 v[36:37], v[46:47], v[30:31]
	v_lshlrev_b32_e32 v41, 16, v26
	v_pk_add_f32 v[32:33], v[32:33], v[36:37]
	s_nop 1
	v_mov_b32_dpp v37, v33 quad_perm:[1,0,3,2] row_mask:0xf bank_mask:0xf
	v_mov_b32_dpp v36, v32 quad_perm:[1,0,3,2] row_mask:0xf bank_mask:0xf
	v_and_b32_e32 v39, 0xffff0000, v26
	v_lshlrev_b32_e32 v43, 16, v27
	v_lshlrev_b32_e32 v40, 16, v28
	v_and_b32_e32 v38, 0xffff0000, v28
	s_waitcnt lgkmcnt(0)
	v_pk_add_f32 v[32:33], v[32:33], v[36:37]
	s_nop 1
	v_mov_b32_dpp v37, v33 quad_perm:[2,3,0,1] row_mask:0xf bank_mask:0xf
	v_mov_b32_dpp v36, v32 quad_perm:[2,3,0,1] row_mask:0xf bank_mask:0xf
	v_lshlrev_b32_e32 v42, 16, v29
	v_and_b32_e32 v27, 0xffff0000, v27
	v_and_b32_e32 v26, 0xffff0000, v29
	v_pk_add_f32 v[28:29], v[40:41], v[38:39]
	s_waitcnt lgkmcnt(0)
	v_pk_add_f32 v[32:33], v[32:33], v[36:37]
	s_nop 1
	v_mov_b32_dpp v37, v33 row_half_mirror row_mask:0xf bank_mask:0xf
	v_mov_b32_dpp v36, v32 row_half_mirror row_mask:0xf bank_mask:0xf
	s_waitcnt lgkmcnt(0)
	v_pk_add_f32 v[32:33], v[32:33], v[36:37]
	s_nop 1
	v_mov_b32_dpp v37, v33 row_mirror row_mask:0xf bank_mask:0xf
	v_mov_b32_dpp v36, v32 row_mirror row_mask:0xf bank_mask:0xf
	s_waitcnt lgkmcnt(0)
	v_pk_add_f32 v[32:33], v[32:33], v[36:37]
	v_mov_b32_e32 v37, v33
	s_nop 1
	v_permlane16_swap_b32_e32 v33, v37
	v_mov_b32_e32 v36, v32
	s_nop 1
	v_permlane16_swap_b32_e32 v32, v36
	s_waitcnt lgkmcnt(0)
	v_pk_add_f32 v[32:33], v[32:33], v[36:37]
	v_mov_b32_e32 v37, v33
	s_nop 1
	v_permlane32_swap_b32_e32 v33, v37
	v_mov_b32_e32 v36, v32
	s_nop 1
	v_permlane32_swap_b32_e32 v32, v36
	s_waitcnt lgkmcnt(0)
	v_pk_add_f32 v[48:49], v[32:33], v[36:37]
	s_nop 0
	v_pk_fma_f32 v[36:37], v[48:49], s[12:13], v[34:35] op_sel_hi:[1,0,1] neg_lo:[1,0,0] neg_hi:[1,0,0]
	v_pk_fma_f32 v[34:35], v[48:49], s[12:13], v[44:45] op_sel_hi:[1,0,1] neg_lo:[1,0,0] neg_hi:[1,0,0]
	v_pk_add_f32 v[44:45], v[42:43], v[26:27]
	v_pk_fma_f32 v[30:31], v[48:49], s[12:13], v[30:31] op_sel_hi:[1,0,1] neg_lo:[1,0,0] neg_hi:[1,0,0]
	v_pk_add_f32 v[28:29], v[28:29], v[44:45]
	s_nop 1
	v_mov_b32_dpp v45, v29 quad_perm:[1,0,3,2] row_mask:0xf bank_mask:0xf
	v_mov_b32_dpp v44, v28 quad_perm:[1,0,3,2] row_mask:0xf bank_mask:0xf
	v_pk_fma_f32 v[32:33], v[48:49], s[12:13], v[46:47] op_sel_hi:[1,0,1] neg_lo:[1,0,0] neg_hi:[1,0,0]
	s_waitcnt lgkmcnt(0)
	v_pk_add_f32 v[28:29], v[28:29], v[44:45]
	s_nop 1
	v_mov_b32_dpp v45, v29 quad_perm:[2,3,0,1] row_mask:0xf bank_mask:0xf
	v_mov_b32_dpp v44, v28 quad_perm:[2,3,0,1] row_mask:0xf bank_mask:0xf
	s_waitcnt lgkmcnt(0)
	v_pk_add_f32 v[28:29], v[28:29], v[44:45]
	s_nop 1
	v_mov_b32_dpp v45, v29 row_half_mirror row_mask:0xf bank_mask:0xf
	v_mov_b32_dpp v44, v28 row_half_mirror row_mask:0xf bank_mask:0xf
	s_waitcnt lgkmcnt(0)
	v_pk_add_f32 v[28:29], v[28:29], v[44:45]
	s_nop 1
	v_mov_b32_dpp v45, v29 row_mirror row_mask:0xf bank_mask:0xf
	v_mov_b32_dpp v44, v28 row_mirror row_mask:0xf bank_mask:0xf
	s_waitcnt lgkmcnt(0)
	v_pk_add_f32 v[28:29], v[28:29], v[44:45]
	v_mov_b32_e32 v45, v29
	s_nop 1
	v_permlane16_swap_b32_e32 v29, v45
	v_mov_b32_e32 v44, v28
	s_nop 1
	v_permlane16_swap_b32_e32 v28, v44
	s_waitcnt lgkmcnt(0)
	v_pk_add_f32 v[28:29], v[28:29], v[44:45]
	v_mov_b32_e32 v45, v29
	s_nop 1
	v_permlane32_swap_b32_e32 v29, v45
	v_mov_b32_e32 v44, v28
	s_nop 1
	v_permlane32_swap_b32_e32 v28, v44
	s_waitcnt lgkmcnt(0)
	v_pk_add_f32 v[44:45], v[28:29], v[44:45]
	s_nop 0
	v_pk_fma_f32 v[40:41], v[44:45], s[12:13], v[40:41] op_sel_hi:[1,0,1] neg_lo:[1,0,0] neg_hi:[1,0,0]
	v_pk_fma_f32 v[38:39], v[44:45], s[12:13], v[38:39] op_sel_hi:[1,0,1] neg_lo:[1,0,0] neg_hi:[1,0,0]
	v_pk_fma_f32 v[28:29], v[44:45], s[12:13], v[42:43] op_sel_hi:[1,0,1] neg_lo:[1,0,0] neg_hi:[1,0,0]
	v_pk_fma_f32 v[26:27], v[44:45], s[12:13], v[26:27] op_sel_hi:[1,0,1] neg_lo:[1,0,0] neg_hi:[1,0,0]
	v_pk_mul_f32 v[42:43], v[34:35], v[34:35]
	v_pk_mul_f32 v[44:45], v[30:31], v[30:31]
	v_pk_fma_f32 v[42:43], v[36:37], v[36:37], v[42:43]
	v_pk_fma_f32 v[44:45], v[32:33], v[32:33], v[44:45]
	v_pk_mul_f32 v[46:47], v[26:27], v[26:27]
	v_pk_add_f32 v[42:43], v[42:43], v[44:45]
	s_nop 1
	v_mov_b32_dpp v45, v43 quad_perm:[1,0,3,2] row_mask:0xf bank_mask:0xf
	v_mov_b32_dpp v44, v42 quad_perm:[1,0,3,2] row_mask:0xf bank_mask:0xf
	v_pk_fma_f32 v[46:47], v[28:29], v[28:29], v[46:47]
	s_waitcnt lgkmcnt(0)
	v_pk_add_f32 v[42:43], v[42:43], v[44:45]
	s_nop 1
	v_mov_b32_dpp v45, v43 quad_perm:[2,3,0,1] row_mask:0xf bank_mask:0xf
	v_mov_b32_dpp v44, v42 quad_perm:[2,3,0,1] row_mask:0xf bank_mask:0xf
	s_waitcnt lgkmcnt(0)
	v_pk_add_f32 v[42:43], v[42:43], v[44:45]
	s_nop 1
	v_mov_b32_dpp v45, v43 row_half_mirror row_mask:0xf bank_mask:0xf
	v_mov_b32_dpp v44, v42 row_half_mirror row_mask:0xf bank_mask:0xf
	s_waitcnt lgkmcnt(0)
	v_pk_add_f32 v[42:43], v[42:43], v[44:45]
	s_nop 1
	v_mov_b32_dpp v45, v43 row_mirror row_mask:0xf bank_mask:0xf
	v_mov_b32_dpp v44, v42 row_mirror row_mask:0xf bank_mask:0xf
	s_waitcnt lgkmcnt(0)
	v_pk_add_f32 v[42:43], v[42:43], v[44:45]
	v_mov_b32_e32 v45, v43
	s_nop 1
	v_permlane16_swap_b32_e32 v43, v45
	v_mov_b32_e32 v44, v42
	s_nop 1
	v_permlane16_swap_b32_e32 v42, v44
	s_waitcnt lgkmcnt(0)
	v_pk_add_f32 v[42:43], v[42:43], v[44:45]
	v_pk_mul_f32 v[44:45], v[38:39], v[38:39]
	v_mov_b32_e32 v49, v43
	s_nop 1
	v_permlane32_swap_b32_e32 v43, v49
	v_pk_fma_f32 v[44:45], v[40:41], v[40:41], v[44:45]
	v_mov_b32_e32 v48, v42
	s_nop 1
	v_permlane32_swap_b32_e32 v42, v48
	v_pk_add_f32 v[44:45], v[44:45], v[46:47]
	s_nop 1
	v_mov_b32_dpp v47, v45 quad_perm:[1,0,3,2] row_mask:0xf bank_mask:0xf
	v_mov_b32_dpp v46, v44 quad_perm:[1,0,3,2] row_mask:0xf bank_mask:0xf
	s_waitcnt lgkmcnt(0)
	v_pk_add_f32 v[44:45], v[44:45], v[46:47]
	s_nop 1
	v_mov_b32_dpp v47, v45 quad_perm:[2,3,0,1] row_mask:0xf bank_mask:0xf
	v_mov_b32_dpp v46, v44 quad_perm:[2,3,0,1] row_mask:0xf bank_mask:0xf
	s_waitcnt lgkmcnt(0)
	v_pk_add_f32 v[44:45], v[44:45], v[46:47]
	s_nop 1
	v_mov_b32_dpp v47, v45 row_half_mirror row_mask:0xf bank_mask:0xf
	v_mov_b32_dpp v46, v44 row_half_mirror row_mask:0xf bank_mask:0xf
	s_waitcnt lgkmcnt(0)
	v_pk_add_f32 v[44:45], v[44:45], v[46:47]
	s_nop 1
	v_mov_b32_dpp v47, v45 row_mirror row_mask:0xf bank_mask:0xf
	v_mov_b32_dpp v46, v44 row_mirror row_mask:0xf bank_mask:0xf
	s_waitcnt lgkmcnt(0)
	v_pk_add_f32 v[44:45], v[44:45], v[46:47]
	v_mov_b32_e32 v47, v45
	s_nop 1
	v_permlane16_swap_b32_e32 v45, v47
	v_mov_b32_e32 v46, v44
	s_nop 1
	v_permlane16_swap_b32_e32 v44, v46
	s_waitcnt lgkmcnt(0)
	v_pk_add_f32 v[44:45], v[44:45], v[46:47]
	v_mov_b32_e32 v47, v45
	s_nop 1
	v_permlane32_swap_b32_e32 v45, v47
	v_mov_b32_e32 v46, v44
	s_nop 1
	v_permlane32_swap_b32_e32 v44, v46
	s_and_saveexec_b64 s[8:9], vcc
	s_cbranch_execz .LBB0_272
	s_mov_b32 s0, 0x358637bd
	v_pk_add_f32 v[42:43], v[42:43], v[48:49]
	v_mov_b64_e32 v[48:49], s[0:1]
	v_pk_fma_f32 v[42:43], v[42:43], s[12:13], v[48:49] op_sel_hi:[1,0,0]
	s_movk_i32 s11, 0x110
	v_mul_f32_e32 v50, 0x4b800000, v43
	v_cmp_gt_f32_e64 s[0:1], s34, v43
	s_nop 1
	v_cndmask_b32_e64 v43, v43, v50, s[0:1]
	v_rsq_f32_e32 v43, v43
	v_mov_b32_e32 v50, s10
	v_mad_u32_u24 v50, v59, s11, v50
	v_mul_f32_e32 v51, 0x45800000, v43
	v_cndmask_b32_e64 v43, v43, v51, s[0:1]
	v_mul_f32_e32 v37, v37, v43
	v_mul_f32_e32 v35, v35, v43
	v_mul_f32_e32 v33, v33, v43
	s_waitcnt vmcnt(0)
	v_fma_f32 v37, v4, v37, v8
	v_fma_f32 v35, v5, v35, v9
	v_fma_f32 v33, v6, v33, v10
	v_cvt_pk_bf16_f32 v37, v37, v2
	ds_write_b16 v50, v37 offset:8
	v_cvt_pk_bf16_f32 v35, v35, v2
	ds_write_b16 v50, v35 offset:280
	v_cvt_pk_bf16_f32 v33, v33, v2
	ds_write_b16 v50, v33 offset:552
	v_mul_f32_e32 v33, 0x4b800000, v42
	v_cmp_gt_f32_e64 s[0:1], s34, v42
	v_mul_f32_e32 v31, v31, v43
	v_fma_f32 v31, v7, v31, v11
	v_cndmask_b32_e64 v33, v42, v33, s[0:1]
	v_rsq_f32_e32 v33, v33
	v_cvt_pk_bf16_f32 v31, v31, v2
	ds_write_b16 v50, v31 offset:824
	v_mul_f32_e32 v31, 0x45800000, v33
	v_cndmask_b32_e64 v31, v33, v31, s[0:1]
	v_mul_f32_e32 v33, v36, v31
	v_fma_f32 v33, v4, v33, v8
	v_cvt_pk_bf16_f32 v33, v33, v2
	ds_write_b16 v50, v33 offset:10
	v_mul_f32_e32 v33, v34, v31
	v_mul_f32_e32 v32, v32, v31
	v_fma_f32 v33, v5, v33, v9
	v_fma_f32 v32, v6, v32, v10
	v_cvt_pk_bf16_f32 v33, v33, v2
	ds_write_b16 v50, v33 offset:282
	v_cvt_pk_bf16_f32 v32, v32, v2
	ds_write_b16 v50, v32 offset:554
	v_mul_f32_e32 v32, v30, v31
	s_waitcnt lgkmcnt(7)
	v_pk_add_f32 v[30:31], v[44:45], v[46:47]
	v_fma_f32 v32, v7, v32, v11
	v_pk_fma_f32 v[30:31], v[30:31], s[12:13], v[48:49] op_sel_hi:[1,0,0]
	v_cvt_pk_bf16_f32 v32, v32, v2
	ds_write_b16 v50, v32 offset:826
	v_mul_f32_e32 v33, 0x4b800000, v31
	v_cmp_gt_f32_e64 s[0:1], s34, v31
	s_nop 1
	v_cndmask_b32_e64 v31, v31, v33, s[0:1]
	v_rsq_f32_e32 v31, v31
	s_nop 0
	v_mul_f32_e32 v32, 0x45800000, v31
	v_cndmask_b32_e64 v31, v31, v32, s[0:1]
	v_mul_f32_e32 v32, v41, v31
	v_fma_f32 v32, v4, v32, v8
	v_cvt_pk_bf16_f32 v32, v32, v2
	ds_write_b16 v50, v32 offset:12
	v_mul_f32_e32 v32, v39, v31
	v_mul_f32_e32 v29, v29, v31
	v_fma_f32 v32, v5, v32, v9
	v_fma_f32 v29, v6, v29, v10
	v_cvt_pk_bf16_f32 v32, v32, v2
	ds_write_b16 v50, v32 offset:284
	v_cvt_pk_bf16_f32 v29, v29, v2
	ds_write_b16 v50, v29 offset:556
	v_mul_f32_e32 v29, 0x4b800000, v30
	v_cmp_gt_f32_e64 s[0:1], s34, v30
	v_mul_f32_e32 v27, v27, v31
	v_fma_f32 v27, v7, v27, v11
	v_cndmask_b32_e64 v29, v30, v29, s[0:1]
	v_rsq_f32_e32 v29, v29
	v_cvt_pk_bf16_f32 v27, v27, v2
	ds_write_b16 v50, v27 offset:828
	v_mul_f32_e32 v27, 0x45800000, v29
	v_cndmask_b32_e64 v27, v29, v27, s[0:1]
	v_mul_f32_e32 v29, v40, v27
	v_fma_f32 v29, v4, v29, v8
	v_cvt_pk_bf16_f32 v29, v29, v2
	ds_write_b16 v50, v29 offset:14
	v_mul_f32_e32 v29, v38, v27
	v_mul_f32_e32 v28, v28, v27
	v_mul_f32_e32 v26, v26, v27
	v_fma_f32 v29, v5, v29, v9
	v_fma_f32 v28, v6, v28, v10
	v_fma_f32 v26, v7, v26, v11
	v_cvt_pk_bf16_f32 v29, v29, v2
	ds_write_b16 v50, v29 offset:286
	v_cvt_pk_bf16_f32 v28, v28, v2
	ds_write_b16 v50, v28 offset:558
	v_cvt_pk_bf16_f32 v26, v26, v2
	ds_write_b16 v50, v26 offset:830
.LBB0_272:
	s_or_b64 exec, exec, s[8:9]
	v_lshlrev_b32_e32 v27, 16, v22
	v_and_b32_e32 v37, 0xffff0000, v22
	v_lshlrev_b32_e32 v39, 16, v23
	v_lshlrev_b32_e32 v26, 16, v24
	v_and_b32_e32 v36, 0xffff0000, v24
	v_lshlrev_b32_e32 v38, 16, v25
	v_and_b32_e32 v23, 0xffff0000, v23
	v_and_b32_e32 v22, 0xffff0000, v25
	v_pk_add_f32 v[24:25], v[26:27], v[36:37]
	v_pk_add_f32 v[28:29], v[38:39], v[22:23]
	v_lshlrev_b32_e32 v33, 16, v18
	v_pk_add_f32 v[24:25], v[24:25], v[28:29]
	s_nop 1
	v_mov_b32_dpp v29, v25 quad_perm:[1,0,3,2] row_mask:0xf bank_mask:0xf
	v_mov_b32_dpp v28, v24 quad_perm:[1,0,3,2] row_mask:0xf bank_mask:0xf
	v_and_b32_e32 v31, 0xffff0000, v18
	v_lshlrev_b32_e32 v35, 16, v19
	v_lshlrev_b32_e32 v32, 16, v20
	v_and_b32_e32 v30, 0xffff0000, v20
	s_waitcnt lgkmcnt(0)
	v_pk_add_f32 v[24:25], v[24:25], v[28:29]
	s_nop 1
	v_mov_b32_dpp v29, v25 quad_perm:[2,3,0,1] row_mask:0xf bank_mask:0xf
	v_mov_b32_dpp v28, v24 quad_perm:[2,3,0,1] row_mask:0xf bank_mask:0xf
	v_lshlrev_b32_e32 v34, 16, v21
	v_and_b32_e32 v19, 0xffff0000, v19
	v_and_b32_e32 v18, 0xffff0000, v21
	v_pk_add_f32 v[20:21], v[32:33], v[30:31]
	s_waitcnt lgkmcnt(0)
	v_pk_add_f32 v[24:25], v[24:25], v[28:29]
	s_nop 1
	v_mov_b32_dpp v29, v25 row_half_mirror row_mask:0xf bank_mask:0xf
	v_mov_b32_dpp v28, v24 row_half_mirror row_mask:0xf bank_mask:0xf
	s_waitcnt lgkmcnt(0)
	v_pk_add_f32 v[24:25], v[24:25], v[28:29]
	s_nop 1
	v_mov_b32_dpp v29, v25 row_mirror row_mask:0xf bank_mask:0xf
	v_mov_b32_dpp v28, v24 row_mirror row_mask:0xf bank_mask:0xf
	s_waitcnt lgkmcnt(0)
	v_pk_add_f32 v[24:25], v[24:25], v[28:29]
	v_mov_b32_e32 v29, v25
	s_nop 1
	v_permlane16_swap_b32_e32 v25, v29
	v_mov_b32_e32 v28, v24
	s_nop 1
	v_permlane16_swap_b32_e32 v24, v28
	s_waitcnt lgkmcnt(0)
	v_pk_add_f32 v[24:25], v[24:25], v[28:29]
	v_mov_b32_e32 v29, v25
	s_nop 1
	v_permlane32_swap_b32_e32 v25, v29
	v_mov_b32_e32 v28, v24
	s_nop 1
	v_permlane32_swap_b32_e32 v24, v28
	s_waitcnt lgkmcnt(0)
	v_pk_add_f32 v[40:41], v[24:25], v[28:29]
	s_nop 0
	v_pk_fma_f32 v[28:29], v[40:41], s[12:13], v[26:27] op_sel_hi:[1,0,1] neg_lo:[1,0,0] neg_hi:[1,0,0]
	v_pk_fma_f32 v[26:27], v[40:41], s[12:13], v[36:37] op_sel_hi:[1,0,1] neg_lo:[1,0,0] neg_hi:[1,0,0]
	v_pk_add_f32 v[36:37], v[34:35], v[18:19]
	v_pk_fma_f32 v[22:23], v[40:41], s[12:13], v[22:23] op_sel_hi:[1,0,1] neg_lo:[1,0,0] neg_hi:[1,0,0]
	v_pk_add_f32 v[20:21], v[20:21], v[36:37]
	s_nop 1
	v_mov_b32_dpp v37, v21 quad_perm:[1,0,3,2] row_mask:0xf bank_mask:0xf
	v_mov_b32_dpp v36, v20 quad_perm:[1,0,3,2] row_mask:0xf bank_mask:0xf
	v_pk_fma_f32 v[24:25], v[40:41], s[12:13], v[38:39] op_sel_hi:[1,0,1] neg_lo:[1,0,0] neg_hi:[1,0,0]
	s_waitcnt lgkmcnt(0)
	v_pk_add_f32 v[20:21], v[20:21], v[36:37]
	s_nop 1
	v_mov_b32_dpp v37, v21 quad_perm:[2,3,0,1] row_mask:0xf bank_mask:0xf
	v_mov_b32_dpp v36, v20 quad_perm:[2,3,0,1] row_mask:0xf bank_mask:0xf
	s_waitcnt lgkmcnt(0)
	v_pk_add_f32 v[20:21], v[20:21], v[36:37]
	s_nop 1
	v_mov_b32_dpp v37, v21 row_half_mirror row_mask:0xf bank_mask:0xf
	v_mov_b32_dpp v36, v20 row_half_mirror row_mask:0xf bank_mask:0xf
	s_waitcnt lgkmcnt(0)
	v_pk_add_f32 v[20:21], v[20:21], v[36:37]
	s_nop 1
	v_mov_b32_dpp v37, v21 row_mirror row_mask:0xf bank_mask:0xf
	v_mov_b32_dpp v36, v20 row_mirror row_mask:0xf bank_mask:0xf
	s_waitcnt lgkmcnt(0)
	v_pk_add_f32 v[20:21], v[20:21], v[36:37]
	v_mov_b32_e32 v37, v21
	s_nop 1
	v_permlane16_swap_b32_e32 v21, v37
	v_mov_b32_e32 v36, v20
	s_nop 1
	v_permlane16_swap_b32_e32 v20, v36
	s_waitcnt lgkmcnt(0)
	v_pk_add_f32 v[20:21], v[20:21], v[36:37]
	v_mov_b32_e32 v37, v21
	s_nop 1
	v_permlane32_swap_b32_e32 v21, v37
	v_mov_b32_e32 v36, v20
	s_nop 1
	v_permlane32_swap_b32_e32 v20, v36
	s_waitcnt lgkmcnt(0)
	v_pk_add_f32 v[36:37], v[20:21], v[36:37]
	s_nop 0
	v_pk_fma_f32 v[32:33], v[36:37], s[12:13], v[32:33] op_sel_hi:[1,0,1] neg_lo:[1,0,0] neg_hi:[1,0,0]
	v_pk_fma_f32 v[30:31], v[36:37], s[12:13], v[30:31] op_sel_hi:[1,0,1] neg_lo:[1,0,0] neg_hi:[1,0,0]
	v_pk_fma_f32 v[20:21], v[36:37], s[12:13], v[34:35] op_sel_hi:[1,0,1] neg_lo:[1,0,0] neg_hi:[1,0,0]
	v_pk_fma_f32 v[18:19], v[36:37], s[12:13], v[18:19] op_sel_hi:[1,0,1] neg_lo:[1,0,0] neg_hi:[1,0,0]
	v_pk_mul_f32 v[34:35], v[26:27], v[26:27]
	v_pk_mul_f32 v[36:37], v[22:23], v[22:23]
	v_pk_fma_f32 v[34:35], v[28:29], v[28:29], v[34:35]
	v_pk_fma_f32 v[36:37], v[24:25], v[24:25], v[36:37]
	v_pk_mul_f32 v[38:39], v[18:19], v[18:19]
	v_pk_add_f32 v[34:35], v[34:35], v[36:37]
	s_nop 1
	v_mov_b32_dpp v37, v35 quad_perm:[1,0,3,2] row_mask:0xf bank_mask:0xf
	v_mov_b32_dpp v36, v34 quad_perm:[1,0,3,2] row_mask:0xf bank_mask:0xf
	v_pk_fma_f32 v[38:39], v[20:21], v[20:21], v[38:39]
	s_waitcnt lgkmcnt(0)
	v_pk_add_f32 v[34:35], v[34:35], v[36:37]
	s_nop 1
	v_mov_b32_dpp v37, v35 quad_perm:[2,3,0,1] row_mask:0xf bank_mask:0xf
	v_mov_b32_dpp v36, v34 quad_perm:[2,3,0,1] row_mask:0xf bank_mask:0xf
	s_waitcnt lgkmcnt(0)
	v_pk_add_f32 v[34:35], v[34:35], v[36:37]
	s_nop 1
	v_mov_b32_dpp v37, v35 row_half_mirror row_mask:0xf bank_mask:0xf
	v_mov_b32_dpp v36, v34 row_half_mirror row_mask:0xf bank_mask:0xf
	s_waitcnt lgkmcnt(0)
	v_pk_add_f32 v[34:35], v[34:35], v[36:37]
	s_nop 1
	v_mov_b32_dpp v37, v35 row_mirror row_mask:0xf bank_mask:0xf
	v_mov_b32_dpp v36, v34 row_mirror row_mask:0xf bank_mask:0xf
	s_waitcnt lgkmcnt(0)
	v_pk_add_f32 v[34:35], v[34:35], v[36:37]
	v_mov_b32_e32 v37, v35
	s_nop 1
	v_permlane16_swap_b32_e32 v35, v37
	v_mov_b32_e32 v36, v34
	s_nop 1
	v_permlane16_swap_b32_e32 v34, v36
	s_waitcnt lgkmcnt(0)
	v_pk_add_f32 v[34:35], v[34:35], v[36:37]
	v_pk_mul_f32 v[36:37], v[30:31], v[30:31]
	v_mov_b32_e32 v41, v35
	s_nop 1
	v_permlane32_swap_b32_e32 v35, v41
	v_pk_fma_f32 v[36:37], v[32:33], v[32:33], v[36:37]
	v_mov_b32_e32 v40, v34
	s_nop 1
	v_permlane32_swap_b32_e32 v34, v40
	v_pk_add_f32 v[36:37], v[36:37], v[38:39]
	s_nop 1
	v_mov_b32_dpp v39, v37 quad_perm:[1,0,3,2] row_mask:0xf bank_mask:0xf
	v_mov_b32_dpp v38, v36 quad_perm:[1,0,3,2] row_mask:0xf bank_mask:0xf
	s_waitcnt lgkmcnt(0)
	v_pk_add_f32 v[36:37], v[36:37], v[38:39]
	s_nop 1
	v_mov_b32_dpp v39, v37 quad_perm:[2,3,0,1] row_mask:0xf bank_mask:0xf
	v_mov_b32_dpp v38, v36 quad_perm:[2,3,0,1] row_mask:0xf bank_mask:0xf
	s_waitcnt lgkmcnt(0)
	v_pk_add_f32 v[36:37], v[36:37], v[38:39]
	s_nop 1
	v_mov_b32_dpp v39, v37 row_half_mirror row_mask:0xf bank_mask:0xf
	v_mov_b32_dpp v38, v36 row_half_mirror row_mask:0xf bank_mask:0xf
	s_waitcnt lgkmcnt(0)
	v_pk_add_f32 v[36:37], v[36:37], v[38:39]
	s_nop 1
	v_mov_b32_dpp v39, v37 row_mirror row_mask:0xf bank_mask:0xf
	v_mov_b32_dpp v38, v36 row_mirror row_mask:0xf bank_mask:0xf
	s_waitcnt lgkmcnt(0)
	v_pk_add_f32 v[36:37], v[36:37], v[38:39]
	v_mov_b32_e32 v39, v37
	s_nop 1
	v_permlane16_swap_b32_e32 v37, v39
	v_mov_b32_e32 v38, v36
	s_nop 1
	v_permlane16_swap_b32_e32 v36, v38
	s_waitcnt lgkmcnt(0)
	v_pk_add_f32 v[36:37], v[36:37], v[38:39]
	v_mov_b32_e32 v39, v37
	s_nop 1
	v_permlane32_swap_b32_e32 v37, v39
	v_mov_b32_e32 v38, v36
	s_nop 1
	v_permlane32_swap_b32_e32 v36, v38
	s_and_saveexec_b64 s[8:9], vcc
	s_cbranch_execz .LBB0_274
	s_mov_b32 s0, 0x358637bd
	v_pk_add_f32 v[34:35], v[34:35], v[40:41]
	v_mov_b64_e32 v[40:41], s[0:1]
	v_pk_fma_f32 v[34:35], v[34:35], s[12:13], v[40:41] op_sel_hi:[1,0,0]
	s_movk_i32 s11, 0x110
	v_mul_f32_e32 v42, 0x4b800000, v35
	v_cmp_gt_f32_e64 s[0:1], s34, v35
	s_nop 1
	v_cndmask_b32_e64 v35, v35, v42, s[0:1]
	v_rsq_f32_e32 v35, v35
	v_mov_b32_e32 v42, s10
	v_mad_u32_u24 v42, v59, s11, v42
	v_mul_f32_e32 v43, 0x45800000, v35
	v_cndmask_b32_e64 v35, v35, v43, s[0:1]
	v_mul_f32_e32 v29, v29, v35
	v_mul_f32_e32 v27, v27, v35
	v_mul_f32_e32 v25, v25, v35
	s_waitcnt vmcnt(0)
	v_fma_f32 v29, v4, v29, v8
	v_fma_f32 v27, v5, v27, v9
	v_fma_f32 v25, v6, v25, v10
	v_cvt_pk_bf16_f32 v29, v29, v2
	ds_write_b16 v42, v29 offset:16
	v_cvt_pk_bf16_f32 v27, v27, v2
	ds_write_b16 v42, v27 offset:288
	v_cvt_pk_bf16_f32 v25, v25, v2
	ds_write_b16 v42, v25 offset:560
	v_mul_f32_e32 v25, 0x4b800000, v34
	v_cmp_gt_f32_e64 s[0:1], s34, v34
	v_mul_f32_e32 v23, v23, v35
	v_fma_f32 v23, v7, v23, v11
	v_cndmask_b32_e64 v25, v34, v25, s[0:1]
	v_rsq_f32_e32 v25, v25
	v_cvt_pk_bf16_f32 v23, v23, v2
	ds_write_b16 v42, v23 offset:832
	v_mul_f32_e32 v23, 0x45800000, v25
	v_cndmask_b32_e64 v23, v25, v23, s[0:1]
	v_mul_f32_e32 v25, v28, v23
	v_fma_f32 v25, v4, v25, v8
	v_cvt_pk_bf16_f32 v25, v25, v2
	ds_write_b16 v42, v25 offset:18
	v_mul_f32_e32 v25, v26, v23
	v_mul_f32_e32 v24, v24, v23
	v_fma_f32 v25, v5, v25, v9
	v_fma_f32 v24, v6, v24, v10
	v_cvt_pk_bf16_f32 v25, v25, v2
	ds_write_b16 v42, v25 offset:290
	v_cvt_pk_bf16_f32 v24, v24, v2
	ds_write_b16 v42, v24 offset:562
	v_mul_f32_e32 v24, v22, v23
	s_waitcnt lgkmcnt(7)
	v_pk_add_f32 v[22:23], v[36:37], v[38:39]
	v_fma_f32 v24, v7, v24, v11
	v_pk_fma_f32 v[22:23], v[22:23], s[12:13], v[40:41] op_sel_hi:[1,0,0]
	v_cvt_pk_bf16_f32 v24, v24, v2
	ds_write_b16 v42, v24 offset:834
	v_mul_f32_e32 v25, 0x4b800000, v23
	v_cmp_gt_f32_e64 s[0:1], s34, v23
	s_nop 1
	v_cndmask_b32_e64 v23, v23, v25, s[0:1]
	v_rsq_f32_e32 v23, v23
	s_nop 0
	v_mul_f32_e32 v24, 0x45800000, v23
	v_cndmask_b32_e64 v23, v23, v24, s[0:1]
	v_mul_f32_e32 v24, v33, v23
	v_fma_f32 v24, v4, v24, v8
	v_cvt_pk_bf16_f32 v24, v24, v2
	ds_write_b16 v42, v24 offset:20
	v_mul_f32_e32 v24, v31, v23
	v_mul_f32_e32 v21, v21, v23
	v_fma_f32 v24, v5, v24, v9
	v_fma_f32 v21, v6, v21, v10
	v_cvt_pk_bf16_f32 v24, v24, v2
	ds_write_b16 v42, v24 offset:292
	v_cvt_pk_bf16_f32 v21, v21, v2
	ds_write_b16 v42, v21 offset:564
	v_mul_f32_e32 v21, 0x4b800000, v22
	v_cmp_gt_f32_e64 s[0:1], s34, v22
	v_mul_f32_e32 v19, v19, v23
	v_fma_f32 v19, v7, v19, v11
	v_cndmask_b32_e64 v21, v22, v21, s[0:1]
	v_rsq_f32_e32 v21, v21
	v_cvt_pk_bf16_f32 v19, v19, v2
	ds_write_b16 v42, v19 offset:836
	v_mul_f32_e32 v19, 0x45800000, v21
	v_cndmask_b32_e64 v19, v21, v19, s[0:1]
	v_mul_f32_e32 v21, v32, v19
	v_fma_f32 v21, v4, v21, v8
	v_cvt_pk_bf16_f32 v21, v21, v2
	ds_write_b16 v42, v21 offset:22
	v_mul_f32_e32 v21, v30, v19
	v_mul_f32_e32 v20, v20, v19
	v_mul_f32_e32 v18, v18, v19
	v_fma_f32 v21, v5, v21, v9
	v_fma_f32 v20, v6, v20, v10
	v_fma_f32 v18, v7, v18, v11
	v_cvt_pk_bf16_f32 v21, v21, v2
	ds_write_b16 v42, v21 offset:294
	v_cvt_pk_bf16_f32 v20, v20, v2
	ds_write_b16 v42, v20 offset:566
	v_cvt_pk_bf16_f32 v18, v18, v2
	ds_write_b16 v42, v18 offset:838
.LBB0_274:
	s_or_b64 exec, exec, s[8:9]
	v_lshlrev_b32_e32 v19, 16, v14
	v_and_b32_e32 v29, 0xffff0000, v14
	v_lshlrev_b32_e32 v31, 16, v15
	v_lshlrev_b32_e32 v18, 16, v16
	v_and_b32_e32 v28, 0xffff0000, v16
	v_lshlrev_b32_e32 v30, 16, v17
	v_and_b32_e32 v15, 0xffff0000, v15
	v_and_b32_e32 v14, 0xffff0000, v17
	v_pk_add_f32 v[16:17], v[18:19], v[28:29]
	v_pk_add_f32 v[20:21], v[30:31], v[14:15]
	s_waitcnt vmcnt(0)
	v_lshlrev_b32_e32 v25, 16, v0
	v_pk_add_f32 v[16:17], v[16:17], v[20:21]
	s_nop 1
	v_mov_b32_dpp v21, v17 quad_perm:[1,0,3,2] row_mask:0xf bank_mask:0xf
	v_mov_b32_dpp v20, v16 quad_perm:[1,0,3,2] row_mask:0xf bank_mask:0xf
	v_and_b32_e32 v23, 0xffff0000, v0
	v_lshlrev_b32_e32 v27, 16, v1
	v_lshlrev_b32_e32 v24, 16, v12
	v_and_b32_e32 v22, 0xffff0000, v12
	s_waitcnt lgkmcnt(0)
	v_pk_add_f32 v[16:17], v[16:17], v[20:21]
	s_nop 1
	v_mov_b32_dpp v21, v17 quad_perm:[2,3,0,1] row_mask:0xf bank_mask:0xf
	v_mov_b32_dpp v20, v16 quad_perm:[2,3,0,1] row_mask:0xf bank_mask:0xf
	v_lshlrev_b32_e32 v26, 16, v13
	v_and_b32_e32 v1, 0xffff0000, v1
	v_and_b32_e32 v0, 0xffff0000, v13
	v_pk_add_f32 v[12:13], v[24:25], v[22:23]
	s_waitcnt lgkmcnt(0)
	v_pk_add_f32 v[16:17], v[16:17], v[20:21]
	s_nop 1
	v_mov_b32_dpp v21, v17 row_half_mirror row_mask:0xf bank_mask:0xf
	v_mov_b32_dpp v20, v16 row_half_mirror row_mask:0xf bank_mask:0xf
	s_waitcnt lgkmcnt(0)
	v_pk_add_f32 v[16:17], v[16:17], v[20:21]
	s_nop 1
	v_mov_b32_dpp v21, v17 row_mirror row_mask:0xf bank_mask:0xf
	v_mov_b32_dpp v20, v16 row_mirror row_mask:0xf bank_mask:0xf
	s_waitcnt lgkmcnt(0)
	v_pk_add_f32 v[16:17], v[16:17], v[20:21]
	v_mov_b32_e32 v21, v17
	s_nop 1
	v_permlane16_swap_b32_e32 v17, v21
	v_mov_b32_e32 v20, v16
	s_nop 1
	v_permlane16_swap_b32_e32 v16, v20
	s_waitcnt lgkmcnt(0)
	v_pk_add_f32 v[16:17], v[16:17], v[20:21]
	v_mov_b32_e32 v21, v17
	s_nop 1
	v_permlane32_swap_b32_e32 v17, v21
	v_mov_b32_e32 v20, v16
	s_nop 1
	v_permlane32_swap_b32_e32 v16, v20
	s_waitcnt lgkmcnt(0)
	v_pk_add_f32 v[32:33], v[16:17], v[20:21]
	s_nop 0
	v_pk_fma_f32 v[20:21], v[32:33], s[12:13], v[18:19] op_sel_hi:[1,0,1] neg_lo:[1,0,0] neg_hi:[1,0,0]
	v_pk_fma_f32 v[18:19], v[32:33], s[12:13], v[28:29] op_sel_hi:[1,0,1] neg_lo:[1,0,0] neg_hi:[1,0,0]
	v_pk_add_f32 v[28:29], v[26:27], v[0:1]
	v_pk_fma_f32 v[14:15], v[32:33], s[12:13], v[14:15] op_sel_hi:[1,0,1] neg_lo:[1,0,0] neg_hi:[1,0,0]
	v_pk_add_f32 v[12:13], v[12:13], v[28:29]
	s_nop 1
	v_mov_b32_dpp v29, v13 quad_perm:[1,0,3,2] row_mask:0xf bank_mask:0xf
	v_mov_b32_dpp v28, v12 quad_perm:[1,0,3,2] row_mask:0xf bank_mask:0xf
	v_pk_fma_f32 v[16:17], v[32:33], s[12:13], v[30:31] op_sel_hi:[1,0,1] neg_lo:[1,0,0] neg_hi:[1,0,0]
	s_waitcnt lgkmcnt(0)
	v_pk_add_f32 v[12:13], v[12:13], v[28:29]
	s_nop 1
	v_mov_b32_dpp v29, v13 quad_perm:[2,3,0,1] row_mask:0xf bank_mask:0xf
	v_mov_b32_dpp v28, v12 quad_perm:[2,3,0,1] row_mask:0xf bank_mask:0xf
	s_waitcnt lgkmcnt(0)
	v_pk_add_f32 v[12:13], v[12:13], v[28:29]
	s_nop 1
	v_mov_b32_dpp v29, v13 row_half_mirror row_mask:0xf bank_mask:0xf
	v_mov_b32_dpp v28, v12 row_half_mirror row_mask:0xf bank_mask:0xf
	s_waitcnt lgkmcnt(0)
	v_pk_add_f32 v[12:13], v[12:13], v[28:29]
	s_nop 1
	v_mov_b32_dpp v29, v13 row_mirror row_mask:0xf bank_mask:0xf
	v_mov_b32_dpp v28, v12 row_mirror row_mask:0xf bank_mask:0xf
	s_waitcnt lgkmcnt(0)
	v_pk_add_f32 v[12:13], v[12:13], v[28:29]
	v_mov_b32_e32 v29, v13
	s_nop 1
	v_permlane16_swap_b32_e32 v13, v29
	v_mov_b32_e32 v28, v12
	s_nop 1
	v_permlane16_swap_b32_e32 v12, v28
	s_waitcnt lgkmcnt(0)
	v_pk_add_f32 v[12:13], v[12:13], v[28:29]
	v_mov_b32_e32 v29, v13
	s_nop 1
	v_permlane32_swap_b32_e32 v13, v29
	v_mov_b32_e32 v28, v12
	s_nop 1
	v_permlane32_swap_b32_e32 v12, v28
	s_waitcnt lgkmcnt(0)
	v_pk_add_f32 v[28:29], v[12:13], v[28:29]
	s_nop 0
	v_pk_fma_f32 v[24:25], v[28:29], s[12:13], v[24:25] op_sel_hi:[1,0,1] neg_lo:[1,0,0] neg_hi:[1,0,0]
	v_pk_fma_f32 v[22:23], v[28:29], s[12:13], v[22:23] op_sel_hi:[1,0,1] neg_lo:[1,0,0] neg_hi:[1,0,0]
	v_pk_fma_f32 v[12:13], v[28:29], s[12:13], v[26:27] op_sel_hi:[1,0,1] neg_lo:[1,0,0] neg_hi:[1,0,0]
	v_pk_fma_f32 v[0:1], v[28:29], s[12:13], v[0:1] op_sel_hi:[1,0,1] neg_lo:[1,0,0] neg_hi:[1,0,0]
	v_pk_mul_f32 v[26:27], v[18:19], v[18:19]
	v_pk_mul_f32 v[28:29], v[14:15], v[14:15]
	v_pk_fma_f32 v[26:27], v[20:21], v[20:21], v[26:27]
	v_pk_fma_f32 v[28:29], v[16:17], v[16:17], v[28:29]
	v_pk_mul_f32 v[30:31], v[0:1], v[0:1]
	v_pk_add_f32 v[26:27], v[26:27], v[28:29]
	s_nop 1
	v_mov_b32_dpp v29, v27 quad_perm:[1,0,3,2] row_mask:0xf bank_mask:0xf
	v_mov_b32_dpp v28, v26 quad_perm:[1,0,3,2] row_mask:0xf bank_mask:0xf
	v_pk_fma_f32 v[30:31], v[12:13], v[12:13], v[30:31]
	s_waitcnt lgkmcnt(0)
	v_pk_add_f32 v[26:27], v[26:27], v[28:29]
	s_nop 1
	v_mov_b32_dpp v29, v27 quad_perm:[2,3,0,1] row_mask:0xf bank_mask:0xf
	v_mov_b32_dpp v28, v26 quad_perm:[2,3,0,1] row_mask:0xf bank_mask:0xf
	s_waitcnt lgkmcnt(0)
	v_pk_add_f32 v[26:27], v[26:27], v[28:29]
	s_nop 1
	v_mov_b32_dpp v29, v27 row_half_mirror row_mask:0xf bank_mask:0xf
	v_mov_b32_dpp v28, v26 row_half_mirror row_mask:0xf bank_mask:0xf
	s_waitcnt lgkmcnt(0)
	v_pk_add_f32 v[26:27], v[26:27], v[28:29]
	s_nop 1
	v_mov_b32_dpp v29, v27 row_mirror row_mask:0xf bank_mask:0xf
	v_mov_b32_dpp v28, v26 row_mirror row_mask:0xf bank_mask:0xf
	s_waitcnt lgkmcnt(0)
	v_pk_add_f32 v[26:27], v[26:27], v[28:29]
	v_mov_b32_e32 v29, v27
	s_nop 1
	v_permlane16_swap_b32_e32 v27, v29
	v_mov_b32_e32 v28, v26
	s_nop 1
	v_permlane16_swap_b32_e32 v26, v28
	s_waitcnt lgkmcnt(0)
	v_pk_add_f32 v[26:27], v[26:27], v[28:29]
	v_pk_mul_f32 v[28:29], v[22:23], v[22:23]
	v_mov_b32_e32 v33, v27
	s_nop 1
	v_permlane32_swap_b32_e32 v27, v33
	v_pk_fma_f32 v[28:29], v[24:25], v[24:25], v[28:29]
	v_mov_b32_e32 v32, v26
	s_nop 1
	v_permlane32_swap_b32_e32 v26, v32
	v_pk_add_f32 v[28:29], v[28:29], v[30:31]
	s_nop 1
	v_mov_b32_dpp v31, v29 quad_perm:[1,0,3,2] row_mask:0xf bank_mask:0xf
	v_mov_b32_dpp v30, v28 quad_perm:[1,0,3,2] row_mask:0xf bank_mask:0xf
	s_waitcnt lgkmcnt(0)
	v_pk_add_f32 v[28:29], v[28:29], v[30:31]
	s_nop 1
	v_mov_b32_dpp v31, v29 quad_perm:[2,3,0,1] row_mask:0xf bank_mask:0xf
	v_mov_b32_dpp v30, v28 quad_perm:[2,3,0,1] row_mask:0xf bank_mask:0xf
	s_waitcnt lgkmcnt(0)
	v_pk_add_f32 v[28:29], v[28:29], v[30:31]
	s_nop 1
	v_mov_b32_dpp v31, v29 row_half_mirror row_mask:0xf bank_mask:0xf
	v_mov_b32_dpp v30, v28 row_half_mirror row_mask:0xf bank_mask:0xf
	s_waitcnt lgkmcnt(0)
	v_pk_add_f32 v[28:29], v[28:29], v[30:31]
	s_nop 1
	v_mov_b32_dpp v31, v29 row_mirror row_mask:0xf bank_mask:0xf
	v_mov_b32_dpp v30, v28 row_mirror row_mask:0xf bank_mask:0xf
	s_waitcnt lgkmcnt(0)
	v_pk_add_f32 v[28:29], v[28:29], v[30:31]
	v_mov_b32_e32 v31, v29
	s_nop 1
	v_permlane16_swap_b32_e32 v29, v31
	v_mov_b32_e32 v30, v28
	s_nop 1
	v_permlane16_swap_b32_e32 v28, v30
	s_waitcnt lgkmcnt(0)
	v_pk_add_f32 v[28:29], v[28:29], v[30:31]
	v_mov_b32_e32 v31, v29
	s_nop 1
	v_permlane32_swap_b32_e32 v29, v31
	v_mov_b32_e32 v30, v28
	s_nop 1
	v_permlane32_swap_b32_e32 v28, v30
	s_and_saveexec_b64 s[0:1], vcc
	s_cbranch_execz .LBB0_276
	s_mov_b32 s8, 0x358637bd
	v_pk_add_f32 v[26:27], v[26:27], v[32:33]
	v_mov_b64_e32 v[32:33], s[8:9]
	v_pk_fma_f32 v[26:27], v[26:27], s[12:13], v[32:33] op_sel_hi:[1,0,0]
	s_movk_i32 s8, 0x110
	v_mul_f32_e32 v34, 0x4b800000, v27
	v_cmp_gt_f32_e32 vcc, s34, v27
	s_nop 1
	v_cndmask_b32_e32 v27, v27, v34, vcc
	v_rsq_f32_e32 v27, v27
	v_mov_b32_e32 v34, s10
	v_mad_u32_u24 v34, v59, s8, v34
	v_mul_f32_e32 v35, 0x45800000, v27
	v_cndmask_b32_e32 v27, v27, v35, vcc
	v_mul_f32_e32 v21, v21, v27
	v_mul_f32_e32 v19, v19, v27
	v_mul_f32_e32 v17, v17, v27
	v_fma_f32 v21, v4, v21, v8
	v_fma_f32 v19, v5, v19, v9
	v_fma_f32 v17, v6, v17, v10
	v_cvt_pk_bf16_f32 v21, v21, v2
	ds_write_b16 v34, v21 offset:24
	v_cvt_pk_bf16_f32 v19, v19, v2
	ds_write_b16 v34, v19 offset:296
	v_cvt_pk_bf16_f32 v17, v17, v2
	ds_write_b16 v34, v17 offset:568
	v_mul_f32_e32 v17, 0x4b800000, v26
	v_cmp_gt_f32_e32 vcc, s34, v26
	v_mul_f32_e32 v15, v15, v27
	v_fma_f32 v15, v7, v15, v11
	v_cndmask_b32_e32 v17, v26, v17, vcc
	v_rsq_f32_e32 v17, v17
	v_cvt_pk_bf16_f32 v15, v15, v2
	ds_write_b16 v34, v15 offset:840
	v_mul_f32_e32 v15, 0x45800000, v17
	v_cndmask_b32_e32 v15, v17, v15, vcc
	v_mul_f32_e32 v17, v20, v15
	v_fma_f32 v17, v4, v17, v8
	v_cvt_pk_bf16_f32 v17, v17, v2
	ds_write_b16 v34, v17 offset:26
	v_mul_f32_e32 v17, v18, v15
	v_mul_f32_e32 v16, v16, v15
	v_fma_f32 v17, v5, v17, v9
	v_fma_f32 v16, v6, v16, v10
	v_cvt_pk_bf16_f32 v17, v17, v2
	ds_write_b16 v34, v17 offset:298
	v_cvt_pk_bf16_f32 v16, v16, v2
	ds_write_b16 v34, v16 offset:570
	v_mul_f32_e32 v16, v14, v15
	s_waitcnt lgkmcnt(7)
	v_pk_add_f32 v[14:15], v[28:29], v[30:31]
	v_fma_f32 v16, v7, v16, v11
	v_pk_fma_f32 v[14:15], v[14:15], s[12:13], v[32:33] op_sel_hi:[1,0,0]
	v_cvt_pk_bf16_f32 v16, v16, v2
	ds_write_b16 v34, v16 offset:842
	v_mul_f32_e32 v17, 0x4b800000, v15
	v_cmp_gt_f32_e32 vcc, s34, v15
	s_nop 1
	v_cndmask_b32_e32 v15, v15, v17, vcc
	v_rsq_f32_e32 v15, v15
	s_nop 0
	v_mul_f32_e32 v16, 0x45800000, v15
	v_cndmask_b32_e32 v15, v15, v16, vcc
	v_mul_f32_e32 v16, v25, v15
	v_fma_f32 v16, v4, v16, v8
	v_cvt_pk_bf16_f32 v16, v16, v2
	ds_write_b16 v34, v16 offset:28
	v_mul_f32_e32 v16, v23, v15
	v_mul_f32_e32 v13, v13, v15
	v_fma_f32 v16, v5, v16, v9
	v_fma_f32 v13, v6, v13, v10
	v_cvt_pk_bf16_f32 v16, v16, v2
	ds_write_b16 v34, v16 offset:300
	v_cvt_pk_bf16_f32 v13, v13, v2
	ds_write_b16 v34, v13 offset:572
	v_mul_f32_e32 v13, 0x4b800000, v14
	v_cmp_gt_f32_e32 vcc, s34, v14
	v_mul_f32_e32 v1, v1, v15
	v_fma_f32 v1, v7, v1, v11
	v_cndmask_b32_e32 v13, v14, v13, vcc
	v_rsq_f32_e32 v13, v13
	v_cvt_pk_bf16_f32 v1, v1, v2
	ds_write_b16 v34, v1 offset:844
	v_mul_f32_e32 v1, 0x45800000, v13
	v_cndmask_b32_e32 v1, v13, v1, vcc
	v_mul_f32_e32 v13, v24, v1
	v_fma_f32 v4, v4, v13, v8
	v_cvt_pk_bf16_f32 v4, v4, v2
	ds_write_b16 v34, v4 offset:30
	v_mul_f32_e32 v4, v22, v1
	v_fma_f32 v4, v5, v4, v9
	v_cvt_pk_bf16_f32 v4, v4, v2
	ds_write_b16 v34, v4 offset:302
	v_mul_f32_e32 v4, v12, v1
	v_fma_f32 v4, v6, v4, v10
	v_mul_f32_e32 v0, v0, v1
	v_cvt_pk_bf16_f32 v4, v4, v2
	ds_write_b16 v34, v4 offset:574
	v_fmac_f32_e32 v11, v7, v0
	v_cvt_pk_bf16_f32 v0, v11, v2
	ds_write_b16 v34, v0 offset:846

.LBB0_350:
	s_waitcnt lgkmcnt(0)
	s_barrier
	s_add_i32 s54, s54, 1
	v_pk_mul_f32 v[10:11], v[10:11], v[220:221]
	v_pk_mul_f32 v[8:9], v[8:9], v[218:219]
	s_add_i32 s53, s53, 32
	s_cmpk_eq_i32 s53, 0x100
	v_mfma_f32_16x16x16_bf16 v[8:11], v[236:237], v[238:239], v[8:11]
	ds_read_b128 v[40:43], v106 offset:23552
	s_waitcnt lgkmcnt(0)
	v_pk_mul_f32 v[0:1], v[42:43], v[42:43]
	v_pk_mul_f32 v[44:45], v[40:41], v[40:41]
	s_nop 0
	v_pk_mov_b32 v[46:47], v[44:45], v[0:1] op_sel:[1,0]
	v_mov_b32_e32 v45, v1
	v_pk_add_f32 v[0:1], v[46:47], v[44:45]
	s_waitcnt vmcnt(12)
	v_lshlrev_b32_e32 v44, 16, v80
	v_add_f32_e32 v0, v0, v1
	v_and_b32_e32 v45, 0xffff0000, v80
	s_nop 0
	v_add_f32_dpp v0, v0, v0 quad_perm:[1,0,3,2] row_mask:0xf bank_mask:0xf
	s_nop 1
	v_add_f32_dpp v0, v0, v0 quad_perm:[2,3,0,1] row_mask:0xf bank_mask:0xf
	s_nop 1
	v_add_f32_dpp v0, v0, v0 row_half_mirror row_mask:0xf bank_mask:0xf
	s_nop 1
	v_add_f32_dpp v0, v0, v0 row_mirror row_mask:0xf bank_mask:0xf
	v_mov_b32_e32 v1, v0
	s_nop 1
	v_permlane16_swap_b32_e32 v0, v1
	v_add_f32_e32 v0, v0, v1
	v_fmamk_f32 v0, v0, 0x3c000000, v178
	v_cmp_gt_f32_e32 vcc, s34, v0
	v_mul_f32_e32 v1, 0x4b800000, v0
	s_nop 0
	v_cndmask_b32_e32 v0, v0, v1, vcc
	v_rsq_f32_e32 v0, v0
	s_nop 0
	v_mul_f32_e32 v1, 0x45800000, v0
	v_cndmask_b32_e32 v0, v0, v1, vcc
	v_pk_mul_f32 v[40:41], v[40:41], v[0:1] op_sel_hi:[1,0]
	v_pk_mul_f32 v[0:1], v[42:43], v[0:1] op_sel_hi:[1,0]
	v_pk_mul_f32 v[40:41], v[4:5], v[40:41]
	v_pk_mul_f32 v[0:1], v[6:7], v[0:1]
	v_lshlrev_b32_e32 v42, 16, v81
	v_and_b32_e32 v43, 0xffff0000, v81
	v_pk_mul_f32 v[40:41], v[40:41], v[44:45]
	v_pk_mul_f32 v[0:1], v[0:1], v[42:43]
	v_cvt_pk_bf16_f32 v40, v40, v41
	v_cvt_pk_bf16_f32 v41, v0, v1
	v_lshlrev_b64 v[0:1], 11, v[78:79]
	v_lshl_add_u64 v[0:1], v[64:65], 0, v[0:1]
	global_store_dwordx2 v[0:1], v[40:41], off
	s_cbranch_scc1 .LBB0_415

.LBB0_363:
	s_waitcnt lgkmcnt(0)
	s_barrier
	ds_read_b128 v[40:43], v93 offset:4352
	ds_read_b128 v[118:121], v93
	ds_read2_b64 v[122:125], v100 offset1:4
	ds_read_b128 v[126:129], v93 offset:4416
	ds_read_b128 v[130:133], v93 offset:64
	ds_read_b128 v[134:137], v93 offset:4480
	v_cvt_pk_bf16_f32 v44, v36, v37
	v_cvt_pk_bf16_f32 v45, v38, v39
	v_cvt_pk_bf16_f32 v46, v32, v33
	s_waitcnt lgkmcnt(4)
	v_mfma_f32_16x16x32_bf16 v[40:43], v[40:43], v[118:121], 0
	v_cvt_pk_bf16_f32 v47, v34, v35
	ds_read2_b64 v[138:141], v100 offset0:8 offset1:12
	ds_read_b128 v[142:145], v93 offset:128
	ds_read_b128 v[158:161], v93 offset:4544
	v_cvt_pk_bf16_f32 v118, v28, v29
	s_waitcnt lgkmcnt(4)
	v_mfma_f32_16x16x32_bf16 v[40:43], v[126:129], v[130:133], v[40:43]
	ds_read_b128 v[130:133], v93 offset:192
	v_cvt_pk_bf16_f32 v119, v30, v31
	v_cvt_pk_bf16_f32 v120, v24, v25
	v_cvt_pk_bf16_f32 v121, v26, v27
	s_waitcnt lgkmcnt(2)
	v_mfma_f32_16x16x32_bf16 v[40:43], v[134:137], v[142:145], v[40:43]
	v_cvt_pk_bf16_f32 v126, v20, v21
	v_cvt_pk_bf16_f32 v127, v22, v23
	v_cvt_pk_bf16_f32 v128, v16, v17
	v_mfma_f32_16x16x32_bf16 v[44:47], v[44:47], v[122:125], 0
	v_cvt_pk_bf16_f32 v129, v18, v19
	ds_read2_b64 v[134:137], v100 offset0:16 offset1:20
	ds_read2_b64 v[122:125], v100 offset0:24 offset1:28
	s_waitcnt lgkmcnt(2)
	v_mfma_f32_16x16x32_bf16 v[40:43], v[158:161], v[130:133], v[40:43]
	v_cvt_pk_bf16_f32 v130, v12, v13
	v_cvt_pk_bf16_f32 v131, v14, v15
	v_cvt_pk_bf16_f32 v132, v8, v9
	v_mfma_f32_16x16x32_bf16 v[44:47], v[118:121], v[138:141], v[44:47]
	v_cvt_pk_bf16_f32 v133, v10, v11
	s_nop 2
	v_cndmask_b32_e64 v0, v40, 0, s[44:45]
	v_cndmask_b32_e64 v1, 0, v41, s[46:47]
	ds_read_b64 v[40:41], v94 offset:14848
	s_waitcnt lgkmcnt(2)
	v_mfma_f32_16x16x32_bf16 v[44:47], v[126:129], v[134:137], v[44:47]
	v_cndmask_b32_e64 v3, v42, 0, s[48:49]
	v_cndmask_b32_e64 v48, v43, 0, s[50:51]
	v_mov_b32_e32 v42, v2
	v_mov_b32_e32 v43, v2
	s_waitcnt lgkmcnt(1)
	v_mfma_f32_16x16x32_bf16 v[44:47], v[130:133], v[122:125], v[44:47]
	v_cvt_pk_bf16_f32 v0, v0, v1
	v_cvt_pk_bf16_f32 v1, v3, v48
	v_mov_b32_e32 v3, v2
	v_add_u32_e32 v118, v66, v96
	s_waitcnt lgkmcnt(0)
	v_mfma_f32_16x16x32_bf16 v[40:43], v[40:43], v[0:3], v[44:47]
	s_nop 2
	v_mov_b32_e32 v44, 0
	s_nop 3
	ds_write_b128 v95, v[40:43] offset:23552
	ds_read_b64 v[238:239], v174 offset:14848
	ds_read_b64 v[222:223], v175 offset:8704
	ds_read_b128 v[190:193], v97 offset:20992
	ds_read_b64 v[224:225], v175 offset:9472
	ds_read_b128 v[194:197], v97 offset:21056
	ds_read_b64 v[226:227], v175 offset:10240
	ds_read_b128 v[198:201], v97 offset:21120
	ds_read_b64 v[228:229], v175 offset:11008
	ds_read_b128 v[202:205], v97 offset:21184
	ds_read_b64 v[230:231], v175 offset:11776
	ds_read_b128 v[206:209], v97 offset:21248
	ds_read_b64 v[232:233], v175 offset:12544
	ds_read_b128 v[210:213], v97 offset:21312
	s_waitcnt lgkmcnt(10)
	v_pk_mul_f32 v[38:39], v[38:39], v[192:193]
	v_pk_mul_f32 v[36:37], v[36:37], v[190:191]
	s_nop 1
	v_mfma_f32_16x16x16_bf16 v[36:39], v[222:223], v[238:239], v[36:39]
	ds_read_b64 v[234:235], v175 offset:13312
	ds_read_b128 v[214:217], v97 offset:21376
	s_waitcnt lgkmcnt(10)
	v_pk_mul_f32 v[34:35], v[34:35], v[196:197]
	v_pk_mul_f32 v[32:33], v[32:33], v[194:195]
	s_nop 1
	v_mfma_f32_16x16x16_bf16 v[32:35], v[224:225], v[238:239], v[32:35]
	ds_read_b64 v[236:237], v175 offset:14080
	ds_read_b128 v[218:221], v97 offset:21440
	s_waitcnt lgkmcnt(10)
	v_pk_mul_f32 v[30:31], v[30:31], v[200:201]
	v_pk_mul_f32 v[28:29], v[28:29], v[198:199]
	s_nop 1
	v_mfma_f32_16x16x16_bf16 v[28:31], v[226:227], v[238:239], v[28:31]
	s_waitcnt lgkmcnt(8)
	v_pk_mul_f32 v[26:27], v[26:27], v[204:205]
	v_pk_mul_f32 v[24:25], v[24:25], v[202:203]
	s_nop 1
	v_mfma_f32_16x16x16_bf16 v[24:27], v[228:229], v[238:239], v[24:27]
	s_waitcnt lgkmcnt(6)
	v_pk_mul_f32 v[22:23], v[22:23], v[208:209]
	v_pk_mul_f32 v[20:21], v[20:21], v[206:207]
	s_nop 1
	v_mfma_f32_16x16x16_bf16 v[20:23], v[230:231], v[238:239], v[20:23]
	s_waitcnt lgkmcnt(4)
	v_pk_mul_f32 v[18:19], v[18:19], v[212:213]
	v_pk_mul_f32 v[16:17], v[16:17], v[210:211]
	s_nop 1
	v_mfma_f32_16x16x16_bf16 v[16:19], v[232:233], v[238:239], v[16:19]
	s_waitcnt lgkmcnt(2)
	v_pk_mul_f32 v[14:15], v[14:15], v[216:217]
	v_pk_mul_f32 v[12:13], v[12:13], v[214:215]
	s_nop 1
	v_mfma_f32_16x16x16_bf16 v[12:15], v[234:235], v[238:239], v[12:15]
	v_mov_b32_e32 v1, 0
	s_waitcnt lgkmcnt(0)
	s_barrier
	v_pk_mul_f32 v[10:11], v[10:11], v[220:221]
	v_pk_mul_f32 v[8:9], v[8:9], v[218:219]
	s_nop 1
	v_mfma_f32_16x16x16_bf16 v[8:11], v[236:237], v[238:239], v[8:11]
	ds_read_b128 v[40:43], v106 offset:23552
	s_waitcnt lgkmcnt(0)
	v_pk_mul_f32 v[44:45], v[42:43], v[42:43]
	v_pk_mul_f32 v[46:47], v[40:41], v[40:41]
	s_nop 0
	v_pk_mov_b32 v[48:49], v[46:47], v[44:45] op_sel:[1,0]
	v_mov_b32_e32 v47, v45
	v_pk_add_f32 v[44:45], v[48:49], v[46:47]
	s_nop 0
	v_add_f32_e32 v0, v44, v45
	s_waitcnt vmcnt(12)
	v_lshlrev_b32_e32 v44, 16, v80
	v_and_b32_e32 v45, 0xffff0000, v80
	v_add_f32_dpp v0, v0, v0 quad_perm:[1,0,3,2] row_mask:0xf bank_mask:0xf
	s_nop 1
	v_add_f32_dpp v0, v0, v0 quad_perm:[2,3,0,1] row_mask:0xf bank_mask:0xf
	s_nop 1
	v_add_f32_dpp v0, v0, v0 row_half_mirror row_mask:0xf bank_mask:0xf
	s_nop 1
	v_add_f32_dpp v0, v0, v0 row_mirror row_mask:0xf bank_mask:0xf
	v_mov_b32_e32 v3, v0
	s_nop 1
	v_permlane16_swap_b32_e32 v0, v3
	v_add_f32_e32 v0, v0, v3
	v_fmamk_f32 v0, v0, 0x3c000000, v178
	v_cmp_gt_f32_e32 vcc, s34, v0
	v_mul_f32_e32 v3, 0x4b800000, v0
	s_nop 0
	v_cndmask_b32_e32 v0, v0, v3, vcc
	v_rsq_f32_e32 v0, v0
	s_nop 0
	v_mul_f32_e32 v3, 0x45800000, v0
	v_cndmask_b32_e32 v0, v0, v3, vcc
	v_pk_mul_f32 v[40:41], v[40:41], v[0:1] op_sel_hi:[1,0]
	v_pk_mul_f32 v[42:43], v[42:43], v[0:1] op_sel_hi:[1,0]
	v_pk_mul_f32 v[40:41], v[4:5], v[40:41]
	v_pk_mul_f32 v[42:43], v[6:7], v[42:43]
	v_pk_mul_f32 v[40:41], v[40:41], v[44:45]
	v_lshlrev_b32_e32 v44, 16, v81
	v_and_b32_e32 v45, 0xffff0000, v81
	v_pk_mul_f32 v[42:43], v[42:43], v[44:45]
	v_cvt_pk_bf16_f32 v40, v40, v41
	v_cvt_pk_bf16_f32 v41, v42, v43
	v_lshlrev_b64 v[42:43], 11, v[78:79]
	v_lshl_add_u64 v[42:43], v[64:65], 0, v[42:43]
	v_add_u32_e32 v78, 16, v78
	global_store_dwordx2 v[42:43], v[40:41], off
	v_mad_i64_i32 v[40:41], s[0:1], v78, s30, v[68:69]
	global_load_dwordx2 v[80:81], v[40:41], off offset:1024
	v_sub_f32_e32 v0, 1.0, v58
	v_max_f32_e32 v112, 0xda24260, v0
	v_sub_f32_e32 v0, 1.0, v59
	v_max_f32_e32 v114, 0xda24260, v0
	v_sub_f32_e32 v0, 1.0, v62
	v_max_f32_e32 v115, 0xda24260, v0
	v_sub_f32_e32 v0, 1.0, v63
	v_max_f32_e32 v116, 0xda24260, v0
	v_lshlrev_b32_e32 v74, 16, v170
	v_lshlrev_b32_e32 v75, 16, v171
	v_lshlrev_b32_e32 v76, 16, v172
	v_lshlrev_b32_e32 v77, 16, v173
	v_cmp_gt_f32_e32 vcc, s34, v112
	s_nop 1
	v_cndmask_b32_e64 v0, 0, 32, vcc
	v_ldexp_f32 v0, v112, v0
	v_log_f32_e32 v0, v0
	s_nop 0
	v_mul_f32_e32 v3, 0x3f317217, v0
	v_fma_f32 v3, v0, s97, -v3
	v_fmac_f32_e32 v3, 0x3377d1cf, v0
	v_fmac_f32_e32 v3, 0x3f317217, v0
	v_cmp_lt_f32_e64 s[0:1], |v0|, s35
	s_nop 1
	v_cndmask_b32_e64 v0, v0, v3, s[0:1]
	v_cndmask_b32_e32 v3, 0, v188, vcc
	v_sub_f32_e32 v0, v0, v3
	v_cmp_gt_f32_e32 vcc, s34, v114
	v_add_f32_e32 v47, 0, v0
	s_nop 0
	v_cndmask_b32_e64 v0, 0, 32, vcc
	v_ldexp_f32 v0, v114, v0
	v_log_f32_e32 v0, v0
	s_nop 0
	v_mul_f32_e32 v3, 0x3f317217, v0
	v_fma_f32 v3, v0, s97, -v3
	v_fmac_f32_e32 v3, 0x3377d1cf, v0
	v_fmac_f32_e32 v3, 0x3f317217, v0
	v_cmp_lt_f32_e64 s[0:1], |v0|, s35
	s_nop 1
	v_cndmask_b32_e64 v0, v0, v3, s[0:1]
	v_cndmask_b32_e32 v3, 0, v188, vcc
	v_sub_f32_e32 v0, v0, v3
	v_cmp_gt_f32_e32 vcc, s34, v115
	v_add_f32_e32 v3, v0, v47
	s_nop 0
	v_cndmask_b32_e64 v0, 0, 32, vcc
	v_ldexp_f32 v0, v115, v0
	v_log_f32_e32 v0, v0
	s_nop 0
	v_mul_f32_e32 v40, 0x3f317217, v0
	v_fma_f32 v40, v0, s97, -v40
	v_fmac_f32_e32 v40, 0x3377d1cf, v0
	v_fmac_f32_e32 v40, 0x3f317217, v0
	v_cmp_lt_f32_e64 s[0:1], |v0|, s35
	s_nop 1
	v_cndmask_b32_e64 v0, v0, v40, s[0:1]
	v_cndmask_b32_e32 v40, 0, v188, vcc
	v_sub_f32_e32 v0, v0, v40
	v_cmp_gt_f32_e32 vcc, s34, v116
	v_add_f32_e32 v46, v0, v3
	s_nop 0
	v_cndmask_b32_e64 v0, 0, 32, vcc
	v_ldexp_f32 v0, v116, v0
	v_log_f32_e32 v0, v0
	s_nop 0
	v_mul_f32_e32 v40, 0x3f317217, v0
	v_fma_f32 v40, v0, s97, -v40
	v_fmac_f32_e32 v40, 0x3377d1cf, v0
	v_fmac_f32_e32 v40, 0x3f317217, v0
	v_cmp_lt_f32_e64 s[0:1], |v0|, s35
	s_nop 1
	v_cndmask_b32_e64 v0, v0, v40, s[0:1]
	v_cndmask_b32_e32 v40, 0, v188, vcc
	v_sub_f32_e32 v0, v0, v40
	v_add_f32_e32 v41, v0, v46
	ds_write_b32 v88, v41 offset:21504
	s_waitcnt lgkmcnt(0)
	s_barrier
	ds_read2st64_b32 v[42:43], v91 offset0:84 offset1:86
	ds_read2st64_b32 v[44:45], v91 offset0:88 offset1:90
	s_and_saveexec_b64 s[0:1], s[40:41]
	s_cbranch_execz .LBB0_389
	v_cmp_lt_i32_e32 vcc, 1, v83
	s_mov_b64 s[10:11], 0
	s_and_saveexec_b64 s[12:13], vcc
	s_xor_b64 s[12:13], exec, s[12:13]
	s_cbranch_execz .LBB0_413
	v_cmp_eq_u32_e32 vcc, 2, v83
	s_mov_b64 s[10:11], -1
	s_and_saveexec_b64 s[14:15], vcc
	s_cbranch_execz .LBB0_385
	s_waitcnt lgkmcnt(1)
	v_add_f32_e32 v1, v42, v43
	s_xor_b64 s[10:11], exec, -1
